# v5 + decode-attention K/V cache shift copy with 16 rows (32 loads) in flight per step
# speedup vs baseline: 1.0205x; 1.0019x over previous
; __device__ __forceinline__ unsigned f2bf(float f) { unsigned u = __builtin_bit_cast(unsigned, f); return (u + 0x7fffu + ((u >> 16) & 1u)) >> 16; }
; __device__ __forceinline__ void attn_task(const P& p, int l, int r, int g, int lane) {
;     ...
;         { const float vv = vdb[(size_t)t * 256];
; #pragma unroll
;           for (int h = 0; h < 4; ++h) o[h] = fmaf(__shfl(p2[h], 0), vv, o[h]); }
;     }
; #pragma unroll
;     for (int h = 0; h < 4; ++h) p.OAb[(size_t)r * 1024 + (g * 4 + h) * 64 + lane] = (bf16)f2bf(o[h] / den[h]);
;     if (s >= 2 && t == 0) {
;         const size_t b0 = ((((size_t)l * 32 + (s - 2)) * 128) * 4 + g) * 64 + lane;
; #pragma unroll 1
;         for (int i0 = 0; i0 < 124; i0 += 4) {
;             float kk[4], vv[4];
; #pragma unroll
;             for (int e = 0; e < 4; ++e) { kk[e] = p.in[2][b0 + (size_t)(i0 + e + 4) * 256]; vv[e] = p.in[3][b0 + (size_t)(i0 + e + 4) * 256]; }
; #pragma unroll
;             for (int e = 0; e < 4; ++e) { p.out[O_SK + b0 + (size_t)(i0 + e) * 256] = kk[e]; p.out[O_SV + b0 + (size_t)(i0 + e) * 256] = vv[e]; }
;         }
.LBB0_1414:
	v_sub_f32_e32 v2, v2, v38
	v_mul_f32_e32 v2, 0x3fb8aa3b, v2
	v_exp_f32_e32 v16, v2
	v_sub_f32_e32 v2, v3, v36
	v_mul_f32_e32 v2, 0x3fb8aa3b, v2
	v_exp_f32_e32 v17, v2
	v_sub_f32_e32 v2, v4, v34
	v_mul_f32_e32 v2, 0x3fb8aa3b, v2
	v_exp_f32_e32 v4, v2
	v_sub_f32_e32 v2, v5, v62
	v_mul_f32_e32 v2, 0x3fb8aa3b, v2
	v_exp_f32_e32 v5, v2
	v_lshl_add_u64 v[2:3], v[8:9], 0, s[36:37]
	s_mov_b32 s23, s35
	v_lshl_add_u64 v[2:3], v[2:3], 0, s[22:23]
	global_load_dword v2, v[2:3], off
	ds_bpermute_b32 v3, v47, v26
	v_add_f32_e32 v18, v30, v32
	v_add_f32_e32 v16, v16, v18
	v_add_f32_e32 v18, v46, v50
	v_add_f32_e32 v17, v17, v18
	v_add_f32_e32 v18, v48, v52
	v_add_f32_e32 v18, v4, v18
	v_add_f32_e32 v4, v49, v54
	v_add_f32_e32 v4, v5, v4
	s_ashr_i32 s17, s16, 31
	s_waitcnt vmcnt(0) lgkmcnt(0)
	v_fmac_f32_e32 v29, v3, v2
	ds_bpermute_b32 v3, v47, v25
	s_waitcnt lgkmcnt(0)
	v_fmac_f32_e32 v24, v3, v2
	ds_bpermute_b32 v3, v47, v27
	s_waitcnt lgkmcnt(0)
	v_fmac_f32_e32 v23, v3, v2
	ds_bpermute_b32 v3, v47, v28
	s_waitcnt lgkmcnt(0)
	v_fmac_f32_e32 v22, v3, v2
	v_div_scale_f32 v2, s[4:5], v16, v16, v29
	v_rcp_f32_e32 v3, v2
	s_lshl_b64 s[4:5], s[16:17], 11
	s_cmp_gt_i32 s49, 1
	v_fma_f32 v5, -v2, v3, 1.0
	v_fmac_f32_e32 v3, v5, v3
	v_div_scale_f32 v5, vcc, v29, v16, v29
	v_mul_f32_e32 v19, v5, v3
	v_fma_f32 v20, -v2, v19, v5
	v_fmac_f32_e32 v19, v20, v3
	v_fma_f32 v2, -v2, v19, v5
	v_div_fmas_f32 v2, v2, v3, v19
	v_div_fixup_f32 v2, v2, v16, v29
	v_bfe_u32 v3, v2, 16, 1
	v_add3_u32 v5, v2, v3, s59
	v_lshl_add_u64 v[2:3], v[14:15], 0, s[4:5]
	global_store_short_d16_hi v[2:3], v5, off
	v_div_scale_f32 v5, s[4:5], v17, v17, v24
	v_rcp_f32_e32 v16, v5
	s_nop 0
	v_fma_f32 v19, -v5, v16, 1.0
	v_fmac_f32_e32 v16, v19, v16
	v_div_scale_f32 v19, vcc, v24, v17, v24
	v_mul_f32_e32 v20, v19, v16
	v_fma_f32 v21, -v5, v20, v19
	v_fmac_f32_e32 v20, v21, v16
	v_fma_f32 v5, -v5, v20, v19
	v_div_fmas_f32 v5, v5, v16, v20
	v_div_fixup_f32 v5, v5, v17, v24
	v_bfe_u32 v16, v5, 16, 1
	v_add3_u32 v5, v5, v16, s59
	global_store_short_d16_hi v[2:3], v5, off offset:128
	v_div_scale_f32 v5, s[4:5], v18, v18, v23
	v_rcp_f32_e32 v16, v5
	s_nop 0
	v_fma_f32 v17, -v5, v16, 1.0
	v_fmac_f32_e32 v16, v17, v16
	v_div_scale_f32 v17, vcc, v23, v18, v23
	v_mul_f32_e32 v19, v17, v16
	v_fma_f32 v20, -v5, v19, v17
	v_fmac_f32_e32 v19, v20, v16
	v_fma_f32 v5, -v5, v19, v17
	v_div_fmas_f32 v5, v5, v16, v19
	v_div_fixup_f32 v5, v5, v18, v23
	v_bfe_u32 v16, v5, 16, 1
	v_add3_u32 v5, v5, v16, s59
	global_store_short_d16_hi v[2:3], v5, off offset:256
	v_div_scale_f32 v5, s[4:5], v4, v4, v22
	v_rcp_f32_e32 v16, v5
	s_cselect_b64 s[4:5], -1, 0
	s_cmp_eq_u32 s56, 0
	s_cselect_b64 s[16:17], -1, 0
	v_fma_f32 v17, -v5, v16, 1.0
	v_fmac_f32_e32 v16, v17, v16
	v_div_scale_f32 v17, vcc, v22, v4, v22
	v_mul_f32_e32 v18, v17, v16
	v_fma_f32 v19, -v5, v18, v17
	v_fmac_f32_e32 v18, v19, v16
	v_fma_f32 v5, -v5, v18, v17
	v_div_fmas_f32 v5, v5, v16, v18
	v_div_fixup_f32 v4, v5, v4, v22
	v_bfe_u32 v5, v4, 16, 1
	s_and_b64 s[4:5], s[16:17], s[4:5]
	v_add3_u32 v4, v4, v5, s59
	s_and_b64 vcc, exec, s[4:5]
	global_store_short_d16_hi v[2:3], v4, off offset:384
	s_cbranch_vccz .LBB0_1201
	s_add_u32 s4, s12, s20
	s_addc_u32 s5, s13, s21
	v_readlane_b32 s60, v249, 44
	s_lshl_b64 s[4:5], s[4:5], 8
	v_readlane_b32 s64, v249, 48
	v_readlane_b32 s65, v249, 49
	s_add_u32 s4, s64, s4
	s_addc_u32 s5, s65, s5
	s_lshl_b64 s[18:19], s[18:19], 17
	s_add_u32 s16, s44, s18
	s_addc_u32 s17, s45, s19
	s_add_u32 s18, s46, s18
	s_addc_u32 s19, s47, s19
	s_mov_b32 s20, -4
	v_readlane_b32 s61, v249, 45
	v_readlane_b32 s62, v249, 46
	v_readlane_b32 s63, v249, 47
	v_readlane_b32 s66, v249, 50
	v_readlane_b32 s67, v249, 51
	v_readlane_b32 s68, v249, 52
	v_readlane_b32 s69, v249, 53
	v_readlane_b32 s70, v249, 54
	v_readlane_b32 s71, v249, 55
	v_readlane_b32 s72, v249, 56
	v_readlane_b32 s73, v249, 57
	v_readlane_b32 s74, v249, 58
	v_readlane_b32 s75, v249, 59
	s_mov_b32 s20, 7
.LBB0_1416:
	s_add_u32 s100, s18, 0x0
	s_addc_u32 s101, s19, 0
	global_load_dword v16, v6, s[100:101] offset:-2048
	global_load_dword v17, v6, s[100:101] offset:-1024
	global_load_dword v18, v6, s[100:101] offset:0
	global_load_dword v19, v6, s[100:101] offset:1024
	s_add_u32 s100, s16, 0x0
	s_addc_u32 s101, s17, 0
	global_load_dword v20, v6, s[100:101] offset:-2048
	global_load_dword v21, v6, s[100:101] offset:-1024
	global_load_dword v22, v6, s[100:101] offset:0
	global_load_dword v23, v6, s[100:101] offset:1024
	s_add_u32 s100, s18, 0x1000
	s_addc_u32 s101, s19, 0
	global_load_dword v24, v6, s[100:101] offset:-2048
	global_load_dword v25, v6, s[100:101] offset:-1024
	global_load_dword v26, v6, s[100:101] offset:0
	global_load_dword v27, v6, s[100:101] offset:1024
	s_add_u32 s100, s16, 0x1000
	s_addc_u32 s101, s17, 0
	global_load_dword v28, v6, s[100:101] offset:-2048
	global_load_dword v29, v6, s[100:101] offset:-1024
	global_load_dword v54, v6, s[100:101] offset:0
	global_load_dword v55, v6, s[100:101] offset:1024
	s_add_u32 s100, s18, 0x2000
	s_addc_u32 s101, s19, 0
	global_load_dword v61, v6, s[100:101] offset:-2048
	global_load_dword v62, v6, s[100:101] offset:-1024
	global_load_dword v63, v6, s[100:101] offset:0
	global_load_dword v64, v6, s[100:101] offset:1024
	s_add_u32 s100, s16, 0x2000
	s_addc_u32 s101, s17, 0
	global_load_dword v65, v6, s[100:101] offset:-2048
	global_load_dword v66, v6, s[100:101] offset:-1024
	global_load_dword v67, v6, s[100:101] offset:0
	global_load_dword v68, v6, s[100:101] offset:1024
	s_add_u32 s100, s18, 0x3000
	s_addc_u32 s101, s19, 0
	global_load_dword v69, v6, s[100:101] offset:-2048
	global_load_dword v70, v6, s[100:101] offset:-1024
	global_load_dword v71, v6, s[100:101] offset:0
	global_load_dword v238, v6, s[100:101] offset:1024
	s_add_u32 s100, s16, 0x3000
	s_addc_u32 s101, s17, 0
	global_load_dword v239, v6, s[100:101] offset:-2048
	global_load_dword v240, v6, s[100:101] offset:-1024
	global_load_dword v241, v6, s[100:101] offset:0
	global_load_dword v242, v6, s[100:101] offset:1024
	s_add_u32 s100, s4, 0x4bf8000
	s_addc_u32 s101, s5, 0
	s_waitcnt vmcnt(28)
; __device__ __forceinline__ void attn_task(const P& p, int l, int r, int g, int lane) {
;     ...
; #pragma unroll 1
;         for (int i0 = 0; i0 < 124; i0 += 4) {
;             float kk[4], vv[4];
; #pragma unroll
;             for (int e = 0; e < 4; ++e) { kk[e] = p.in[2][b0 + (size_t)(i0 + e + 4) * 256]; vv[e] = p.in[3][b0 + (size_t)(i0 + e + 4) * 256]; }
; #pragma unroll
;             for (int e = 0; e < 4; ++e) { p.out[O_SK + b0 + (size_t)(i0 + e) * 256] = kk[e]; p.out[O_SV + b0 + (size_t)(i0 + e) * 256] = vv[e]; }
;         }
	global_store_dword v6, v16, s[100:101] offset:0
	global_store_dword v6, v17, s[100:101] offset:1024
	global_store_dword v6, v18, s[100:101] offset:2048
	global_store_dword v6, v19, s[100:101] offset:3072
	s_add_u32 s100, s4, 0x5bf8000
	s_addc_u32 s101, s5, 0
	s_waitcnt vmcnt(28)
	global_store_dword v6, v20, s[100:101] offset:0
	global_store_dword v6, v21, s[100:101] offset:1024
	global_store_dword v6, v22, s[100:101] offset:2048
	global_store_dword v6, v23, s[100:101] offset:3072
	s_add_u32 s100, s4, 0x4bf9000
	s_addc_u32 s101, s5, 0
	s_waitcnt vmcnt(28)
	global_store_dword v6, v24, s[100:101] offset:0
	global_store_dword v6, v25, s[100:101] offset:1024
	global_store_dword v6, v26, s[100:101] offset:2048
	global_store_dword v6, v27, s[100:101] offset:3072
	s_add_u32 s100, s4, 0x5bf9000
	s_addc_u32 s101, s5, 0
	s_waitcnt vmcnt(28)
	global_store_dword v6, v28, s[100:101] offset:0
	global_store_dword v6, v29, s[100:101] offset:1024
	global_store_dword v6, v54, s[100:101] offset:2048
	global_store_dword v6, v55, s[100:101] offset:3072
	s_add_u32 s100, s4, 0x4bfa000
	s_addc_u32 s101, s5, 0
	s_waitcnt vmcnt(28)
	global_store_dword v6, v61, s[100:101] offset:0
	global_store_dword v6, v62, s[100:101] offset:1024
	global_store_dword v6, v63, s[100:101] offset:2048
	global_store_dword v6, v64, s[100:101] offset:3072
	s_add_u32 s100, s4, 0x5bfa000
	s_addc_u32 s101, s5, 0
	s_waitcnt vmcnt(28)
	global_store_dword v6, v65, s[100:101] offset:0
	global_store_dword v6, v66, s[100:101] offset:1024
	global_store_dword v6, v67, s[100:101] offset:2048
	global_store_dword v6, v68, s[100:101] offset:3072
	s_add_u32 s100, s4, 0x4bfb000
	s_addc_u32 s101, s5, 0
	s_waitcnt vmcnt(28)
	global_store_dword v6, v69, s[100:101] offset:0
	global_store_dword v6, v70, s[100:101] offset:1024
	global_store_dword v6, v71, s[100:101] offset:2048
	global_store_dword v6, v238, s[100:101] offset:3072
	s_add_u32 s100, s4, 0x5bfb000
	s_addc_u32 s101, s5, 0
	s_waitcnt vmcnt(28)
	global_store_dword v6, v239, s[100:101] offset:0
	global_store_dword v6, v240, s[100:101] offset:1024
	global_store_dword v6, v241, s[100:101] offset:2048
	global_store_dword v6, v242, s[100:101] offset:3072
	s_add_u32 s18, s18, 0x4000
	s_addc_u32 s19, s19, 0
	s_add_u32 s16, s16, 0x4000
	s_addc_u32 s17, s17, 0
	s_add_u32 s4, s4, 0x4000
	s_addc_u32 s5, s5, 0
	s_sub_u32 s20, s20, 1
	s_cmp_lg_u32 s20, 0
	s_cbranch_scc1 .LBB0_1416
	s_add_u32 s100, s18, 0x0
	s_addc_u32 s101, s19, 0
	global_load_dword v16, v6, s[100:101] offset:-2048
	global_load_dword v17, v6, s[100:101] offset:-1024
	global_load_dword v18, v6, s[100:101] offset:0
	global_load_dword v19, v6, s[100:101] offset:1024
	s_add_u32 s100, s16, 0x0
	s_addc_u32 s101, s17, 0
	global_load_dword v20, v6, s[100:101] offset:-2048
	global_load_dword v21, v6, s[100:101] offset:-1024
	global_load_dword v22, v6, s[100:101] offset:0
	global_load_dword v23, v6, s[100:101] offset:1024
	s_add_u32 s100, s18, 0x1000
	s_addc_u32 s101, s19, 0
	global_load_dword v24, v6, s[100:101] offset:-2048
	global_load_dword v25, v6, s[100:101] offset:-1024
	global_load_dword v26, v6, s[100:101] offset:0
	global_load_dword v27, v6, s[100:101] offset:1024
	s_add_u32 s100, s16, 0x1000
	s_addc_u32 s101, s17, 0
	global_load_dword v28, v6, s[100:101] offset:-2048
	global_load_dword v29, v6, s[100:101] offset:-1024
	global_load_dword v54, v6, s[100:101] offset:0
	global_load_dword v55, v6, s[100:101] offset:1024
	s_add_u32 s100, s18, 0x2000
	s_addc_u32 s101, s19, 0
	global_load_dword v61, v6, s[100:101] offset:-2048
	global_load_dword v62, v6, s[100:101] offset:-1024
	global_load_dword v63, v6, s[100:101] offset:0
	global_load_dword v64, v6, s[100:101] offset:1024
	s_add_u32 s100, s16, 0x2000
	s_addc_u32 s101, s17, 0
	global_load_dword v65, v6, s[100:101] offset:-2048
	global_load_dword v66, v6, s[100:101] offset:-1024
	global_load_dword v67, v6, s[100:101] offset:0
	global_load_dword v68, v6, s[100:101] offset:1024
	s_add_u32 s100, s4, 0x4bf8000
	s_addc_u32 s101, s5, 0
	s_waitcnt vmcnt(20)
	global_store_dword v6, v16, s[100:101] offset:0
	global_store_dword v6, v17, s[100:101] offset:1024
	global_store_dword v6, v18, s[100:101] offset:2048
	global_store_dword v6, v19, s[100:101] offset:3072
	s_add_u32 s100, s4, 0x5bf8000
	s_addc_u32 s101, s5, 0
	s_waitcnt vmcnt(20)
	global_store_dword v6, v20, s[100:101] offset:0
	global_store_dword v6, v21, s[100:101] offset:1024
	global_store_dword v6, v22, s[100:101] offset:2048
	global_store_dword v6, v23, s[100:101] offset:3072
	s_add_u32 s100, s4, 0x4bf9000
	s_addc_u32 s101, s5, 0
	s_waitcnt vmcnt(20)
	global_store_dword v6, v24, s[100:101] offset:0
	global_store_dword v6, v25, s[100:101] offset:1024
	global_store_dword v6, v26, s[100:101] offset:2048
	global_store_dword v6, v27, s[100:101] offset:3072
	s_add_u32 s100, s4, 0x5bf9000
	s_addc_u32 s101, s5, 0
	s_waitcnt vmcnt(20)
	global_store_dword v6, v28, s[100:101] offset:0
	global_store_dword v6, v29, s[100:101] offset:1024
	global_store_dword v6, v54, s[100:101] offset:2048
	global_store_dword v6, v55, s[100:101] offset:3072
	s_add_u32 s100, s4, 0x4bfa000
	s_addc_u32 s101, s5, 0
	s_waitcnt vmcnt(20)
	global_store_dword v6, v61, s[100:101] offset:0
	global_store_dword v6, v62, s[100:101] offset:1024
	global_store_dword v6, v63, s[100:101] offset:2048
	global_store_dword v6, v64, s[100:101] offset:3072
	s_add_u32 s100, s4, 0x5bfa000
	s_addc_u32 s101, s5, 0
	s_waitcnt vmcnt(20)
	global_store_dword v6, v65, s[100:101] offset:0
	global_store_dword v6, v66, s[100:101] offset:1024
	global_store_dword v6, v67, s[100:101] offset:2048
	global_store_dword v6, v68, s[100:101] offset:3072
	s_branch .LBB0_1201

; __global__ void __launch_bounds__(512, 2) mega(Args a) {
	.amdhsa_kernel _Z4mega4Args
		.amdhsa_group_segment_fixed_size 0
		.amdhsa_private_segment_fixed_size 0
		.amdhsa_kernarg_size 872
		.amdhsa_user_sgpr_count 2
		.amdhsa_user_sgpr_dispatch_ptr 0
		.amdhsa_user_sgpr_queue_ptr 0
		.amdhsa_user_sgpr_kernarg_segment_ptr 1
		.amdhsa_user_sgpr_dispatch_id 0
		.amdhsa_user_sgpr_kernarg_preload_length 0
		.amdhsa_user_sgpr_kernarg_preload_offset 0
		.amdhsa_user_sgpr_private_segment_size 0
		.amdhsa_uses_dynamic_stack 0
		.amdhsa_enable_private_segment 0
		.amdhsa_system_sgpr_workgroup_id_x 1
		.amdhsa_system_sgpr_workgroup_id_y 0
		.amdhsa_system_sgpr_workgroup_id_z 0
		.amdhsa_system_sgpr_workgroup_info 0
		.amdhsa_system_vgpr_workitem_id 0
		.amdhsa_next_free_vgpr 255
		.amdhsa_next_free_sgpr 102
		.amdhsa_accum_offset 256
		.amdhsa_reserve_vcc 1
		.amdhsa_float_round_mode_32 0
		.amdhsa_float_round_mode_16_64 0
		.amdhsa_float_denorm_mode_32 3
		.amdhsa_float_denorm_mode_16_64 3
		.amdhsa_dx10_clamp 1
		.amdhsa_ieee_mode 1
		.amdhsa_fp16_overflow 0
		.amdhsa_tg_split 0
		.amdhsa_exception_fp_ieee_invalid_op 0
		.amdhsa_exception_fp_denorm_src 0
		.amdhsa_exception_fp_ieee_div_zero 0
		.amdhsa_exception_fp_ieee_overflow 0
		.amdhsa_exception_fp_ieee_underflow 0
		.amdhsa_exception_fp_ieee_inexact 0
		.amdhsa_exception_int_div_zero 0
	.end_amdhsa_kernel

; __global__ void __launch_bounds__(512, 2) mega(Args a) {
amdhsa.kernels:
  - .agpr_count:     0
    .args:
      - .offset:         0
        .size:           616
        .value_kind:     by_value
      - .offset:         616
        .size:           4
        .value_kind:     hidden_block_count_x
      - .offset:         620
        .size:           4
        .value_kind:     hidden_block_count_y
      - .offset:         624
        .size:           4
        .value_kind:     hidden_block_count_z
      - .offset:         628
        .size:           2
        .value_kind:     hidden_group_size_x
      - .offset:         630
        .size:           2
        .value_kind:     hidden_group_size_y
      - .offset:         632
        .size:           2
        .value_kind:     hidden_group_size_z
      - .offset:         634
        .size:           2
        .value_kind:     hidden_remainder_x
      - .offset:         636
        .size:           2
        .value_kind:     hidden_remainder_y
      - .offset:         638
        .size:           2
        .value_kind:     hidden_remainder_z
      - .offset:         656
        .size:           8
        .value_kind:     hidden_global_offset_x
      - .offset:         664
        .size:           8
        .value_kind:     hidden_global_offset_y
      - .offset:         672
        .size:           8
        .value_kind:     hidden_global_offset_z
      - .offset:         680
        .size:           2
        .value_kind:     hidden_grid_dims
      - .offset:         736
        .size:           4
        .value_kind:     hidden_dynamic_lds_size
    .group_segment_fixed_size: 0
    .kernarg_segment_align: 8
    .kernarg_segment_size: 872
    .language:       OpenCL C
    .language_version:
      - 2
      - 0
    .max_flat_workgroup_size: 512
    .name:           _Z4mega4Args
    .private_segment_fixed_size: 0
    .sgpr_count:     108
    .sgpr_spill_count: 434
    .symbol:         _Z4mega4Args.kd
    .uniform_work_group_size: 1
    .uses_dynamic_stack: false
    .vgpr_count:     255
    .vgpr_spill_count: 0
    .wavefront_size: 64
